# fused residual+RMSNorm GEMM epilogues (last-layer w_o and final FFN-out): residual-base and gate loads of column groups 2-4 issued 9-10 ahead into free registers with counted vmcnt instead of load->vm
# speedup vs baseline: 1.0231x; 1.0059x over previous
.LBB0_1455:
	s_add_u32 s42, s14, 0x14d80000
	s_addc_u32 s43, s15, 0
	s_lshr_b32 s0, s38, 5
	s_mulk_i32 s0, 0x2400
	s_ashr_i32 s1, s0, 31
	s_lshl_b32 s4, s27, 5
	s_lshl_b64 s[8:9], s[0:1], 2
	s_add_u32 s0, s54, s8
	s_addc_u32 s1, s31, s9
	s_lshl_b32 s5, s40, 8
	v_lshrrev_b32_e32 v112, 2, v187
	s_or_b32 s4, s5, s4
	v_and_b32_e32 v190, 12, v112
	v_or_b32_e32 v162, s4, v190
	v_ashrrev_i32_e32 v163, 31, v162
	v_lshlrev_b64 v[166:167], 2, v[162:163]
	v_lshl_add_u64 v[112:113], s[0:1], 0, v[166:167]
	s_mov_b64 s[0:1], 0x5000
	s_ashr_i32 s39, s38, 31
	v_lshl_add_u64 v[168:169], v[112:113], 0, s[0:1]
	s_movk_i32 s0, 0x5000
	v_add_co_u32_e32 v112, vcc, s0, v112
	s_lshl_b64 s[0:1], s[38:39], 20
	s_add_u32 s0, s60, s0
	v_addc_co_u32_e32 v113, vcc, 0, v113, vcc
	v_ashrrev_i32_e32 v149, 31, v148
	s_addc_u32 s1, s61, s1
	s_barrier
	global_load_dwordx4 v[144:147], v[112:113], off
	v_lshl_add_u64 v[184:185], s[0:1], 0, v[166:167]
	v_lshlrev_b64 v[112:113], 12, v[148:149]
	v_lshl_add_u64 v[170:171], v[184:185], 0, v[112:113]
	global_load_dwordx4 v[112:115], v[170:171], off
	v_or_b32_e32 v164, 16, v148
	v_ashrrev_i32_e32 v165, 31, v164
	v_or_b32_e32 v160, 32, v148
	v_ashrrev_i32_e32 v161, 31, v160
	v_or_b32_e32 v158, 48, v148
	v_ashrrev_i32_e32 v159, 31, v158
	v_add_u32_e32 v150, 0x80, v148
	v_ashrrev_i32_e32 v151, 31, v150
	v_add_u32_e32 v156, 0x90, v148
	v_ashrrev_i32_e32 v157, 31, v156
	v_add_u32_e32 v152, 0xa0, v148
	v_ashrrev_i32_e32 v153, 31, v152
	v_add_u32_e32 v154, 0xb0, v148
	v_ashrrev_i32_e32 v155, 31, v154
	s_lshl_b32 s0, s27, 4
	s_add_i32 s0, s0, 0
	s_lshl_b32 s1, s26, 12
	s_add_i32 s1, s1, s0
	v_readlane_b32 s0, v253, 59
	v_and_b32_e32 v189, 63, v187
	s_mov_b32 s34, s54
	s_mov_b32 s54, s31
	v_cmp_gt_u32_e64 s[6:7], 32, v189
	s_waitcnt vmcnt(0)
	v_pk_fma_f32 v[124:125], v[108:109], v[144:145], v[112:113]
	v_lshlrev_b64 v[108:109], 12, v[164:165]
	v_lshl_add_u64 v[172:173], v[184:185], 0, v[108:109]
	v_pk_fma_f32 v[126:127], v[110:111], v[146:147], v[114:115]
	global_load_dwordx4 v[108:111], v[172:173], off
	s_waitcnt vmcnt(0)
	v_pk_fma_f32 v[120:121], v[104:105], v[144:145], v[108:109]
	v_lshlrev_b64 v[104:105], 12, v[160:161]
	v_lshl_add_u64 v[174:175], v[184:185], 0, v[104:105]
	v_pk_fma_f32 v[122:123], v[106:107], v[146:147], v[110:111]
	global_load_dwordx4 v[104:107], v[174:175], off
	s_waitcnt vmcnt(0)
	v_pk_fma_f32 v[116:117], v[100:101], v[144:145], v[104:105]
	v_lshlrev_b64 v[100:101], 12, v[158:159]
	v_lshl_add_u64 v[176:177], v[184:185], 0, v[100:101]
	v_pk_fma_f32 v[118:119], v[102:103], v[146:147], v[106:107]
	global_load_dwordx4 v[100:103], v[176:177], off
	s_waitcnt vmcnt(0)
	v_pk_fma_f32 v[112:113], v[96:97], v[144:145], v[100:101]
	v_lshlrev_b64 v[96:97], 12, v[150:151]
	v_lshl_add_u64 v[178:179], v[184:185], 0, v[96:97]
	v_pk_fma_f32 v[114:115], v[98:99], v[146:147], v[102:103]
	global_load_dwordx4 v[96:99], v[178:179], off
	s_waitcnt vmcnt(0)
	v_pk_fma_f32 v[108:109], v[92:93], v[144:145], v[96:97]
	v_lshlrev_b64 v[92:93], 12, v[156:157]
	v_lshl_add_u64 v[180:181], v[184:185], 0, v[92:93]
	v_pk_fma_f32 v[110:111], v[94:95], v[146:147], v[98:99]
	global_load_dwordx4 v[92:95], v[180:181], off
	s_waitcnt vmcnt(0)
	v_pk_fma_f32 v[92:93], v[88:89], v[144:145], v[92:93]
	v_lshlrev_b64 v[88:89], 12, v[152:153]
	v_lshl_add_u64 v[182:183], v[184:185], 0, v[88:89]
	v_pk_fma_f32 v[94:95], v[90:91], v[146:147], v[94:95]
	global_load_dwordx4 v[88:91], v[182:183], off
	s_waitcnt vmcnt(0)
	v_pk_fma_f32 v[88:89], v[80:81], v[144:145], v[88:89]
	v_lshlrev_b64 v[80:81], 12, v[154:155]
	v_lshl_add_u64 v[184:185], v[184:185], 0, v[80:81]
	v_pk_fma_f32 v[90:91], v[82:83], v[146:147], v[90:91]
	global_load_dwordx4 v[80:83], v[184:185], off
	s_waitcnt vmcnt(0)
	v_pk_fma_f32 v[106:107], v[66:67], v[146:147], v[82:83]
	v_pk_fma_f32 v[104:105], v[64:65], v[144:145], v[80:81]
	global_store_dwordx4 v[170:171], v[124:127], off
	global_store_dwordx4 v[172:173], v[120:123], off
	global_store_dwordx4 v[174:175], v[116:119], off
	global_store_dwordx4 v[176:177], v[112:115], off
	global_store_dwordx4 v[178:179], v[108:111], off
	global_store_dwordx4 v[180:181], v[92:95], off
	global_store_dwordx4 v[182:183], v[88:91], off
	global_store_dwordx4 v[184:185], v[104:107], off
	global_load_dwordx4 v[192:195], v[168:169], off offset:64
	global_load_dwordx4 v[196:199], v[170:171], off offset:64
	global_load_dwordx4 v[200:203], v[172:173], off offset:64
	global_load_dwordx4 v[204:207], v[174:175], off offset:64
	global_load_dwordx4 v[214:217], v[176:177], off offset:64
	global_load_dwordx4 v[224:227], v[178:179], off offset:64
	global_load_dwordx4 v[228:231], v[180:181], off offset:64
	global_load_dwordx4 v[232:235], v[182:183], off offset:64
	global_load_dwordx4 v[238:241], v[184:185], off offset:64
	global_load_dwordx4 v[248:251], v[168:169], off offset:512
	s_waitcnt vmcnt(8)
	v_pk_fma_f32 v[98:99], v[86:87], v[194:195], v[198:199]
	v_pk_fma_f32 v[96:97], v[84:85], v[192:193], v[196:197]
	s_waitcnt vmcnt(7)
	v_pk_fma_f32 v[102:103], v[78:79], v[194:195], v[202:203]
	v_pk_fma_f32 v[100:101], v[76:77], v[192:193], v[200:201]
	s_waitcnt vmcnt(6)
	v_pk_fma_f32 v[86:87], v[74:75], v[194:195], v[206:207]
	v_pk_fma_f32 v[84:85], v[72:73], v[192:193], v[204:205]
	s_waitcnt vmcnt(5)
	v_pk_fma_f32 v[70:71], v[70:71], v[194:195], v[216:217]
	v_pk_fma_f32 v[68:69], v[68:69], v[192:193], v[214:215]
	s_waitcnt vmcnt(4)
	v_pk_fma_f32 v[62:63], v[62:63], v[194:195], v[226:227]
	v_pk_fma_f32 v[60:61], v[60:61], v[192:193], v[224:225]
	s_waitcnt vmcnt(3)
	v_pk_fma_f32 v[66:67], v[58:59], v[194:195], v[230:231]
	v_pk_fma_f32 v[64:65], v[56:57], v[192:193], v[228:229]
	s_waitcnt vmcnt(2)
	v_pk_fma_f32 v[58:59], v[54:55], v[194:195], v[234:235]
	v_pk_fma_f32 v[56:57], v[52:53], v[192:193], v[232:233]
	s_waitcnt vmcnt(1)
	v_pk_fma_f32 v[78:79], v[42:43], v[194:195], v[240:241]
	v_pk_fma_f32 v[76:77], v[40:41], v[192:193], v[238:239]
	global_load_dwordx4 v[192:195], v[170:171], off offset:512
	global_load_dwordx4 v[196:199], v[172:173], off offset:512
	global_load_dwordx4 v[200:203], v[174:175], off offset:512
	global_load_dwordx4 v[204:207], v[176:177], off offset:512
	global_load_dwordx4 v[214:217], v[178:179], off offset:512
	global_load_dwordx4 v[224:227], v[180:181], off offset:512
	global_load_dwordx4 v[228:231], v[182:183], off offset:512
	global_load_dwordx4 v[232:235], v[184:185], off offset:512
	global_load_dwordx4 v[238:241], v[168:169], off offset:576
	global_store_dwordx4 v[170:171], v[96:99], off offset:64
	global_store_dwordx4 v[172:173], v[100:103], off offset:64
	global_store_dwordx4 v[174:175], v[84:87], off offset:64
	global_store_dwordx4 v[176:177], v[68:71], off offset:64
	global_store_dwordx4 v[178:179], v[60:63], off offset:64
	global_store_dwordx4 v[180:181], v[64:67], off offset:64
	global_store_dwordx4 v[182:183], v[56:59], off offset:64
	global_store_dwordx4 v[184:185], v[76:79], off offset:64
	s_waitcnt vmcnt(0)
	v_pk_fma_f32 v[74:75], v[50:51], v[250:251], v[194:195]
	v_pk_fma_f32 v[72:73], v[48:49], v[248:249], v[192:193]
	s_waitcnt vmcnt(0)
	v_pk_fma_f32 v[82:83], v[46:47], v[250:251], v[198:199]
	v_pk_fma_f32 v[80:81], v[44:45], v[248:249], v[196:197]
	s_waitcnt vmcnt(0)
	v_pk_fma_f32 v[54:55], v[38:39], v[250:251], v[202:203]
	v_pk_fma_f32 v[52:53], v[36:37], v[248:249], v[200:201]
	s_waitcnt vmcnt(0)
	v_pk_fma_f32 v[50:51], v[34:35], v[250:251], v[206:207]
	v_pk_fma_f32 v[48:49], v[32:33], v[248:249], v[204:205]
	s_waitcnt vmcnt(0)
	v_pk_fma_f32 v[38:39], v[26:27], v[250:251], v[216:217]
	v_pk_fma_f32 v[36:37], v[24:25], v[248:249], v[214:215]
	s_waitcnt vmcnt(0)
	v_pk_fma_f32 v[46:47], v[22:23], v[250:251], v[226:227]
	v_pk_fma_f32 v[44:45], v[20:21], v[248:249], v[224:225]
	s_waitcnt vmcnt(0)
	v_pk_fma_f32 v[34:35], v[18:19], v[250:251], v[230:231]
	v_pk_fma_f32 v[32:33], v[16:17], v[248:249], v[228:229]
	s_waitcnt vmcnt(0)
	v_pk_fma_f32 v[42:43], v[14:15], v[250:251], v[234:235]
	v_pk_fma_f32 v[40:41], v[12:13], v[248:249], v[232:233]
	global_load_dwordx4 v[248:251], v[170:171], off offset:576
	global_load_dwordx4 v[192:195], v[172:173], off offset:576
	global_load_dwordx4 v[196:199], v[174:175], off offset:576
	global_load_dwordx4 v[200:203], v[176:177], off offset:576
	global_load_dwordx4 v[204:207], v[178:179], off offset:576
	global_load_dwordx4 v[214:217], v[180:181], off offset:576
	global_load_dwordx4 v[224:227], v[182:183], off offset:576
	global_load_dwordx4 v[228:231], v[184:185], off offset:576
	global_store_dwordx4 v[170:171], v[72:75], off offset:512
	global_store_dwordx4 v[172:173], v[80:83], off offset:512
	global_store_dwordx4 v[174:175], v[52:55], off offset:512
	global_store_dwordx4 v[176:177], v[48:51], off offset:512
	global_store_dwordx4 v[178:179], v[36:39], off offset:512
	global_store_dwordx4 v[180:181], v[44:47], off offset:512
	global_store_dwordx4 v[182:183], v[32:35], off offset:512
	global_store_dwordx4 v[184:185], v[40:43], off offset:512
	s_waitcnt vmcnt(0)
	v_pk_fma_f32 v[30:31], v[30:31], v[240:241], v[250:251]
	v_pk_fma_f32 v[28:29], v[28:29], v[238:239], v[248:249]
	s_waitcnt vmcnt(0)
	v_pk_fma_f32 v[26:27], v[142:143], v[240:241], v[194:195]
	v_pk_fma_f32 v[24:25], v[140:141], v[238:239], v[192:193]
	s_waitcnt vmcnt(0)
	v_pk_fma_f32 v[22:23], v[138:139], v[240:241], v[198:199]
	v_pk_fma_f32 v[20:21], v[136:137], v[238:239], v[196:197]
	s_waitcnt vmcnt(0)
	v_pk_fma_f32 v[18:19], v[134:135], v[240:241], v[202:203]
	v_pk_fma_f32 v[16:17], v[132:133], v[238:239], v[200:201]
	v_mul_f32_e32 v132, v103, v103
	v_fmac_f32_e32 v132, v102, v102
	global_store_dwordx4 v[170:171], v[28:31], off offset:576
	global_store_dwordx4 v[172:173], v[24:27], off offset:576
	global_store_dwordx4 v[174:175], v[20:23], off offset:576
	global_store_dwordx4 v[176:177], v[16:19], off offset:576
	s_waitcnt vmcnt(4)
	v_pk_fma_f32 v[14:15], v[130:131], v[240:241], v[206:207]
	v_pk_fma_f32 v[12:13], v[128:129], v[238:239], v[204:205]
	s_waitcnt vmcnt(0)
	v_pk_fma_f32 v[10:11], v[10:11], v[240:241], v[216:217]
	v_pk_fma_f32 v[8:9], v[8:9], v[238:239], v[214:215]
	s_waitcnt vmcnt(0)
	v_pk_fma_f32 v[6:7], v[6:7], v[240:241], v[226:227]
	v_pk_fma_f32 v[4:5], v[4:5], v[238:239], v[224:225]
	s_waitcnt vmcnt(0)
	v_pk_fma_f32 v[0:1], v[0:1], v[238:239], v[228:229]
	v_mul_f32_e32 v128, v125, v125
	v_mul_f32_e32 v129, v127, v127
	v_fmac_f32_e32 v128, v124, v124
	v_fmac_f32_e32 v129, v126, v126
	v_pk_fma_f32 v[2:3], v[2:3], v[240:241], v[230:231]
	v_add_f32_e32 v128, v128, v129
	v_mul_f32_e32 v129, v97, v97
	v_mul_f32_e32 v130, v99, v99
	v_fmac_f32_e32 v129, v96, v96
	v_fmac_f32_e32 v130, v98, v98
	v_add_f32_e32 v129, v129, v130
	v_add_f32_e32 v128, v128, v129
	v_mul_f32_e32 v129, v73, v73
	v_mul_f32_e32 v130, v75, v75
	v_fmac_f32_e32 v129, v72, v72
	v_fmac_f32_e32 v130, v74, v74
	v_add_f32_e32 v129, v129, v130
	v_add_f32_e32 v128, v128, v129
	v_mul_f32_e32 v129, v29, v29
	v_mul_f32_e32 v130, v31, v31
	v_fmac_f32_e32 v129, v28, v28
	v_fmac_f32_e32 v130, v30, v30
	v_add_f32_e32 v129, v129, v130
	v_mul_f32_e32 v130, v121, v121
	v_mul_f32_e32 v131, v123, v123
	v_fmac_f32_e32 v130, v120, v120
	v_fmac_f32_e32 v131, v122, v122
	v_add_f32_e32 v130, v130, v131
	v_mul_f32_e32 v131, v101, v101
	v_fmac_f32_e32 v131, v100, v100
	v_add_f32_e32 v131, v131, v132
	v_add_f32_e32 v130, v130, v131
	v_mul_f32_e32 v131, v81, v81
	v_mul_f32_e32 v132, v83, v83
	v_fmac_f32_e32 v131, v80, v80
	v_fmac_f32_e32 v132, v82, v82
	v_add_f32_e32 v131, v131, v132
	v_add_f32_e32 v130, v130, v131
	v_mul_f32_e32 v131, v25, v25
	v_mul_f32_e32 v132, v27, v27
	v_fmac_f32_e32 v131, v24, v24
	v_fmac_f32_e32 v132, v26, v26
	v_add_f32_e32 v131, v131, v132
	global_store_dwordx4 v[178:179], v[12:15], off offset:576
	global_store_dwordx4 v[180:181], v[8:11], off offset:576
	global_store_dwordx4 v[182:183], v[4:7], off offset:576
	global_store_dwordx4 v[184:185], v[0:3], off offset:576
	v_add_f32_e32 v129, v128, v129
	v_add3_u32 v128, s1, v190, v188
	v_add_f32_e32 v130, v130, v131
	ds_write2st64_b32 v128, v129, v130 offset1:4
	v_mul_f32_e32 v129, v117, v117
	v_mul_f32_e32 v130, v119, v119
	v_fmac_f32_e32 v129, v116, v116
	v_fmac_f32_e32 v130, v118, v118
	v_add_f32_e32 v129, v129, v130
	v_mul_f32_e32 v130, v85, v85
	v_mul_f32_e32 v131, v87, v87
	v_fmac_f32_e32 v130, v84, v84
	v_fmac_f32_e32 v131, v86, v86
	v_add_f32_e32 v130, v130, v131
	v_add_f32_e32 v129, v129, v130
	v_mul_f32_e32 v130, v53, v53
	v_mul_f32_e32 v131, v55, v55
	v_fmac_f32_e32 v130, v52, v52
	v_fmac_f32_e32 v131, v54, v54
	v_add_f32_e32 v130, v130, v131
	v_add_f32_e32 v129, v129, v130
	v_mul_f32_e32 v130, v21, v21
	v_mul_f32_e32 v131, v23, v23
	v_fmac_f32_e32 v130, v20, v20
	v_fmac_f32_e32 v131, v22, v22
	v_add_f32_e32 v130, v130, v131
	v_add_f32_e32 v129, v129, v130
	v_mul_f32_e32 v130, v113, v113
	v_mul_f32_e32 v131, v115, v115
	v_fmac_f32_e32 v130, v112, v112
	v_fmac_f32_e32 v131, v114, v114
	v_add_f32_e32 v130, v130, v131
	v_mul_f32_e32 v131, v69, v69
	v_mul_f32_e32 v132, v71, v71
	v_fmac_f32_e32 v131, v68, v68
	v_fmac_f32_e32 v132, v70, v70
	v_add_f32_e32 v131, v131, v132
	v_add_f32_e32 v130, v130, v131
	v_mul_f32_e32 v131, v49, v49
	v_mul_f32_e32 v132, v51, v51
	v_fmac_f32_e32 v131, v48, v48
	v_fmac_f32_e32 v132, v50, v50
	v_add_f32_e32 v131, v131, v132
	v_add_f32_e32 v130, v130, v131
	v_mul_f32_e32 v131, v17, v17
	v_mul_f32_e32 v132, v19, v19
	v_fmac_f32_e32 v131, v16, v16
	v_fmac_f32_e32 v132, v18, v18
	v_add_f32_e32 v131, v131, v132
	v_add_f32_e32 v130, v130, v131
	ds_write2st64_b32 v128, v129, v130 offset0:8 offset1:12
	v_mul_f32_e32 v129, v109, v109
	v_mul_f32_e32 v130, v111, v111
	v_fmac_f32_e32 v129, v108, v108
	v_fmac_f32_e32 v130, v110, v110
	v_add_f32_e32 v129, v129, v130
	v_mul_f32_e32 v130, v61, v61
	v_mul_f32_e32 v131, v63, v63
	v_fmac_f32_e32 v130, v60, v60
	v_fmac_f32_e32 v131, v62, v62
	v_add_f32_e32 v130, v130, v131
	v_add_f32_e32 v129, v129, v130
	v_mul_f32_e32 v130, v37, v37
	v_mul_f32_e32 v131, v39, v39
	v_fmac_f32_e32 v130, v36, v36
	v_fmac_f32_e32 v131, v38, v38
	v_add_f32_e32 v130, v130, v131
	v_add_f32_e32 v129, v129, v130
	v_mul_f32_e32 v130, v13, v13
	v_mul_f32_e32 v131, v15, v15
	v_fmac_f32_e32 v130, v12, v12
	v_fmac_f32_e32 v131, v14, v14
	v_add_f32_e32 v130, v130, v131
	v_add_f32_e32 v129, v129, v130
	v_mul_f32_e32 v130, v93, v93
	v_mul_f32_e32 v131, v95, v95
	v_fmac_f32_e32 v130, v92, v92
	v_fmac_f32_e32 v131, v94, v94
	v_add_f32_e32 v130, v130, v131
	v_mul_f32_e32 v131, v65, v65
	v_mul_f32_e32 v132, v67, v67
	v_fmac_f32_e32 v131, v64, v64
	v_fmac_f32_e32 v132, v66, v66
	v_add_f32_e32 v131, v131, v132
	v_add_f32_e32 v130, v130, v131
	v_mul_f32_e32 v131, v45, v45
	v_mul_f32_e32 v132, v47, v47
	v_fmac_f32_e32 v131, v44, v44
	v_fmac_f32_e32 v132, v46, v46
	v_add_f32_e32 v131, v131, v132
	v_add_f32_e32 v130, v130, v131
	v_mul_f32_e32 v131, v9, v9
	v_mul_f32_e32 v132, v11, v11
	v_fmac_f32_e32 v131, v8, v8
	v_fmac_f32_e32 v132, v10, v10
	v_add_f32_e32 v131, v131, v132
	v_add_f32_e32 v130, v130, v131
	ds_write2st64_b32 v128, v129, v130 offset0:32 offset1:36
	v_mul_f32_e32 v129, v89, v89
	v_mul_f32_e32 v130, v91, v91
	v_fmac_f32_e32 v129, v88, v88
	v_fmac_f32_e32 v130, v90, v90
	v_add_f32_e32 v129, v129, v130
	v_mul_f32_e32 v130, v57, v57
	v_mul_f32_e32 v131, v59, v59
	v_fmac_f32_e32 v130, v56, v56
	v_fmac_f32_e32 v131, v58, v58
	v_add_f32_e32 v130, v130, v131
	v_add_f32_e32 v129, v129, v130
	v_mul_f32_e32 v130, v33, v33
	v_mul_f32_e32 v131, v35, v35
	v_fmac_f32_e32 v130, v32, v32
	v_fmac_f32_e32 v131, v34, v34
	v_add_f32_e32 v130, v130, v131
	v_add_f32_e32 v129, v129, v130
	v_mul_f32_e32 v130, v5, v5
	v_mul_f32_e32 v131, v7, v7
	v_fmac_f32_e32 v130, v4, v4
	v_fmac_f32_e32 v131, v6, v6
	v_add_f32_e32 v130, v130, v131
	v_add_f32_e32 v129, v129, v130
	v_mul_f32_e32 v130, v105, v105
	v_mul_f32_e32 v131, v107, v107
	v_fmac_f32_e32 v130, v104, v104
	v_fmac_f32_e32 v131, v106, v106
	v_add_f32_e32 v130, v130, v131
	v_mul_f32_e32 v131, v77, v77
	v_mul_f32_e32 v132, v79, v79
	v_fmac_f32_e32 v131, v76, v76
	v_fmac_f32_e32 v132, v78, v78
	v_add_f32_e32 v131, v131, v132
	v_add_f32_e32 v130, v130, v131
	v_mul_f32_e32 v131, v41, v41
	v_mul_f32_e32 v132, v43, v43
	v_fmac_f32_e32 v131, v40, v40
	v_fmac_f32_e32 v132, v42, v42
	v_add_f32_e32 v131, v131, v132
	v_add_f32_e32 v130, v130, v131
	v_mul_f32_e32 v131, v1, v1
	v_mul_f32_e32 v132, v3, v3
	v_fmac_f32_e32 v131, v0, v0
	v_fmac_f32_e32 v132, v2, v2
	v_add_f32_e32 v131, v131, v132
	v_add_f32_e32 v130, v130, v131
	ds_write2st64_b32 v128, v129, v130 offset0:40 offset1:44
	s_waitcnt lgkmcnt(0)
	s_barrier
	v_and_b32_e32 v128, 31, v187
	v_lshl_or_b32 v130, s0, 5, v128
	v_lshl_add_u32 v128, s38, 8, v130
	s_and_saveexec_b64 s[0:1], s[6:7]
	s_cbranch_execz .LBB0_1457
	v_lshl_add_u32 v129, v130, 6, 0
	ds_read_b128 v[132:135], v129
	ds_read_b128 v[136:139], v129 offset:16
	ds_read_b128 v[140:143], v129 offset:32
	ds_read_b128 v[144:147], v129 offset:48
	s_ashr_i32 s41, s40, 31
	s_waitcnt lgkmcnt(3)
	v_add_f32_e32 v129, 0, v132
	v_add_f32_e32 v129, v129, v133
	v_add_f32_e32 v129, v129, v134
	v_add_f32_e32 v129, v129, v135
	s_waitcnt lgkmcnt(2)
	v_add_f32_e32 v129, v129, v136
	v_add_f32_e32 v129, v129, v137
	v_add_f32_e32 v129, v129, v138
	v_add_f32_e32 v129, v129, v139
	s_waitcnt lgkmcnt(1)
	v_add_f32_e32 v129, v129, v140
	v_add_f32_e32 v129, v129, v141
	v_add_f32_e32 v129, v129, v142
	v_add_f32_e32 v129, v129, v143
	s_waitcnt lgkmcnt(0)
	v_add_f32_e32 v129, v129, v144
	v_add_f32_e32 v129, v129, v145
	v_add_f32_e32 v129, v129, v146
	v_add_f32_e32 v131, v129, v147
	v_ashrrev_i32_e32 v129, 31, v128
	v_lshl_add_u64 v[132:133], v[128:129], 4, s[42:43]
	v_lshl_add_u64 v[132:133], s[40:41], 2, v[132:133]
	global_store_dword v[132:133], v131, off sc1

.LBB0_1736:
	s_add_u32 s0, s36, 0x14dc0000
	s_addc_u32 s1, s37, 0
	s_lshr_b32 s4, s38, 5
	s_mulk_i32 s4, 0x2400
	s_ashr_i32 s5, s4, 31
	s_lshl_b32 s6, s31, 5
	s_lshl_b64 s[4:5], s[4:5], 2
	s_add_u32 s4, s51, s4
	s_addc_u32 s5, s54, s5
	s_lshl_b32 s7, s40, 8
	v_lshrrev_b32_e32 v129, 2, v183
	s_or_b32 s6, s7, s6
	v_and_b32_e32 v186, 12, v129
	v_or_b32_e32 v130, s6, v186
	v_ashrrev_i32_e32 v131, 31, v130
	v_lshlrev_b64 v[130:131], 2, v[130:131]
	v_lshl_add_u64 v[134:135], s[4:5], 0, v[130:131]
	s_mov_b64 s[4:5], 0x8000
	v_lshl_add_u64 v[164:165], v[134:135], 0, s[4:5]
	s_mov_b32 s4, 0x8000
	v_add_co_u32_e32 v134, vcc, s4, v134
	s_barrier
	s_nop 0
	v_addc_co_u32_e32 v135, vcc, 0, v135, vcc
	global_load_dwordx4 v[138:141], v[134:135], off
	s_ashr_i32 s39, s38, 31
	s_lshl_b64 s[4:5], s[38:39], 20
	v_ashrrev_i32_e32 v129, 31, v128
	s_add_u32 s6, s55, s4
	v_lshlrev_b64 v[136:137], 12, v[128:129]
	s_addc_u32 s7, s60, s5
	v_lshl_add_u64 v[134:135], s[6:7], 0, v[136:137]
	v_lshl_add_u64 v[166:167], v[134:135], 0, v[130:131]
	v_lshl_add_u64 v[132:133], v[136:137], 0, s[28:29]
	s_mov_b64 s[4:5], 0x90000
	v_lshl_add_u64 v[134:135], v[136:137], 0, s[4:5]
	s_mov_b64 s[4:5], 0xa0000
	v_and_b32_e32 v185, 63, v183
	s_waitcnt vmcnt(0)
	v_pk_mul_f32 v[188:189], v[140:141], 0.5 op_sel_hi:[1,0]
	v_pk_mul_f32 v[190:191], v[138:139], 0.5 op_sel_hi:[1,0]
	global_load_dwordx4 v[138:141], v[166:167], off
	s_waitcnt vmcnt(0)
	v_pk_fma_f32 v[162:163], v[124:125], v[190:191], v[138:139]
	v_or_b32_e32 v124, 16, v128
	v_ashrrev_i32_e32 v125, 31, v124
	v_lshlrev_b64 v[154:155], 12, v[124:125]
	v_lshl_add_u64 v[124:125], s[6:7], 0, v[154:155]
	v_lshl_add_u64 v[168:169], v[124:125], 0, v[130:131]
	v_pk_fma_f32 v[160:161], v[126:127], v[188:189], v[140:141]
	global_load_dwordx4 v[124:127], v[168:169], off
	s_waitcnt vmcnt(0)
	v_pk_fma_f32 v[158:159], v[120:121], v[190:191], v[124:125]
	v_or_b32_e32 v120, 32, v128
	v_ashrrev_i32_e32 v121, 31, v120
	v_lshlrev_b64 v[142:143], 12, v[120:121]
	v_lshl_add_u64 v[120:121], s[6:7], 0, v[142:143]
	v_lshl_add_u64 v[170:171], v[120:121], 0, v[130:131]
	v_pk_fma_f32 v[156:157], v[122:123], v[188:189], v[126:127]
	global_load_dwordx4 v[120:123], v[170:171], off
	s_waitcnt vmcnt(0)
	v_pk_fma_f32 v[146:147], v[116:117], v[190:191], v[120:121]
	v_or_b32_e32 v116, 48, v128
	v_ashrrev_i32_e32 v117, 31, v116
	v_lshlrev_b64 v[148:149], 12, v[116:117]
	v_lshl_add_u64 v[116:117], s[6:7], 0, v[148:149]
	v_lshl_add_u64 v[172:173], v[116:117], 0, v[130:131]
	v_pk_fma_f32 v[144:145], v[118:119], v[188:189], v[122:123]
	global_load_dwordx4 v[116:119], v[172:173], off
	s_waitcnt vmcnt(0)
	v_pk_fma_f32 v[152:153], v[112:113], v[190:191], v[116:117]
	v_lshl_add_u64 v[112:113], s[6:7], 0, v[132:133]
	v_lshl_add_u64 v[174:175], v[112:113], 0, v[130:131]
	v_pk_fma_f32 v[150:151], v[114:115], v[188:189], v[118:119]
	global_load_dwordx4 v[112:115], v[174:175], off
	s_waitcnt vmcnt(0)
	v_pk_fma_f32 v[126:127], v[104:105], v[190:191], v[112:113]
	v_lshl_add_u64 v[104:105], s[6:7], 0, v[134:135]
	v_lshl_add_u64 v[176:177], v[104:105], 0, v[130:131]
	v_pk_fma_f32 v[124:125], v[106:107], v[188:189], v[114:115]
	global_load_dwordx4 v[104:107], v[176:177], off
	v_lshl_add_u64 v[114:115], v[136:137], 0, s[4:5]
	s_mov_b64 s[4:5], 0xb0000
	v_lshl_add_u64 v[112:113], v[136:137], 0, s[4:5]
	s_lshl_b32 s4, s31, 4
	s_add_i32 s4, s4, 0
	s_lshl_b32 s5, s30, 12
	s_add_i32 s5, s5, s4
	s_waitcnt vmcnt(0)
	v_pk_fma_f32 v[140:141], v[96:97], v[190:191], v[104:105]
	v_lshl_add_u64 v[96:97], s[6:7], 0, v[114:115]
	v_lshl_add_u64 v[178:179], v[96:97], 0, v[130:131]
	v_pk_fma_f32 v[138:139], v[98:99], v[188:189], v[106:107]
	global_load_dwordx4 v[96:99], v[178:179], off
	s_waitcnt vmcnt(0)
	v_pk_fma_f32 v[122:123], v[88:89], v[190:191], v[96:97]
	v_lshl_add_u64 v[88:89], s[6:7], 0, v[112:113]
	v_lshl_add_u64 v[180:181], v[88:89], 0, v[130:131]
	v_pk_fma_f32 v[120:121], v[90:91], v[188:189], v[98:99]
	global_load_dwordx4 v[88:91], v[180:181], off
	v_cmp_gt_u32_e64 s[6:7], 32, v185
	s_waitcnt vmcnt(0)
	v_pk_fma_f32 v[116:117], v[82:83], v[188:189], v[90:91]
	v_pk_fma_f32 v[118:119], v[80:81], v[190:191], v[88:89]
	global_load_dwordx4 v[192:195], v[164:165], off offset:64
	global_load_dwordx4 v[196:199], v[166:167], off offset:64
	global_load_dwordx4 v[200:203], v[168:169], off offset:64
	global_load_dwordx4 v[204:207], v[170:171], off offset:64
	global_load_dwordx4 v[214:217], v[172:173], off offset:64
	global_load_dwordx4 v[224:227], v[174:175], off offset:64
	global_load_dwordx4 v[228:231], v[176:177], off offset:64
	global_load_dwordx4 v[232:235], v[178:179], off offset:64
	global_load_dwordx4 v[238:241], v[180:181], off offset:64
	global_load_dwordx4 v[248:251], v[164:165], off offset:512
	s_waitcnt vmcnt(9)
	v_pk_mul_f32 v[188:189], v[194:195], 0.5 op_sel_hi:[1, 0]
	v_pk_mul_f32 v[190:191], v[192:193], 0.5 op_sel_hi:[1, 0]
	global_load_dwordx4 v[192:195], v[166:167], off offset:512
	s_waitcnt vmcnt(9)
	v_pk_fma_f32 v[104:105], v[110:111], v[188:189], v[198:199]
	v_pk_fma_f32 v[106:107], v[108:109], v[190:191], v[196:197]
	global_load_dwordx4 v[196:199], v[168:169], off offset:512
	s_waitcnt vmcnt(9)
	v_pk_fma_f32 v[102:103], v[102:103], v[188:189], v[202:203]
	v_pk_fma_f32 v[100:101], v[100:101], v[190:191], v[200:201]
	global_load_dwordx4 v[200:203], v[170:171], off offset:512
	s_waitcnt vmcnt(9)
	v_pk_fma_f32 v[94:95], v[94:95], v[188:189], v[206:207]
	v_pk_fma_f32 v[92:93], v[92:93], v[190:191], v[204:205]
	global_load_dwordx4 v[204:207], v[172:173], off offset:512
	s_waitcnt vmcnt(9)
	v_pk_fma_f32 v[96:97], v[86:87], v[188:189], v[216:217]
	v_pk_fma_f32 v[98:99], v[84:85], v[190:191], v[214:215]
	global_load_dwordx4 v[214:217], v[174:175], off offset:512
	s_waitcnt vmcnt(9)
	v_pk_fma_f32 v[84:85], v[78:79], v[188:189], v[226:227]
	v_pk_fma_f32 v[86:87], v[76:77], v[190:191], v[224:225]
	global_load_dwordx4 v[224:227], v[176:177], off offset:512
	s_waitcnt vmcnt(9)
	v_pk_fma_f32 v[88:89], v[70:71], v[188:189], v[230:231]
	v_pk_fma_f32 v[90:91], v[68:69], v[190:191], v[228:229]
	global_load_dwordx4 v[228:231], v[178:179], off offset:512
	s_waitcnt vmcnt(9)
	v_pk_fma_f32 v[80:81], v[66:67], v[188:189], v[234:235]
	v_pk_fma_f32 v[82:83], v[64:65], v[190:191], v[232:233]
	global_load_dwordx4 v[232:235], v[180:181], off offset:512
	s_waitcnt vmcnt(9)
	v_pk_fma_f32 v[76:77], v[58:59], v[188:189], v[240:241]
	v_pk_fma_f32 v[78:79], v[56:57], v[190:191], v[238:239]
	global_load_dwordx4 v[238:241], v[164:165], off offset:576
	s_waitcnt vmcnt(9)
	v_pk_mul_f32 v[108:109], v[250:251], 0.5 op_sel_hi:[1, 0]
	v_pk_mul_f32 v[110:111], v[248:249], 0.5 op_sel_hi:[1, 0]
	global_load_dwordx4 v[248:251], v[166:167], off offset:576
	s_waitcnt vmcnt(9)
	v_pk_fma_f32 v[64:65], v[74:75], v[108:109], v[194:195]
	v_pk_fma_f32 v[66:67], v[72:73], v[110:111], v[192:193]
	global_load_dwordx4 v[192:195], v[168:169], off offset:576
	s_waitcnt vmcnt(9)
	v_pk_fma_f32 v[72:73], v[62:63], v[108:109], v[198:199]
	v_pk_fma_f32 v[74:75], v[60:61], v[110:111], v[196:197]
	global_load_dwordx4 v[196:199], v[170:171], off offset:576
	s_waitcnt vmcnt(9)
	v_pk_fma_f32 v[58:59], v[54:55], v[108:109], v[202:203]
	v_pk_fma_f32 v[62:63], v[52:53], v[110:111], v[200:201]
	global_load_dwordx4 v[200:203], v[172:173], off offset:576
	s_waitcnt vmcnt(9)
	v_pk_fma_f32 v[68:69], v[50:51], v[108:109], v[206:207]
	v_pk_fma_f32 v[70:71], v[48:49], v[110:111], v[204:205]
	global_load_dwordx4 v[204:207], v[180:181], off offset:576
	s_waitcnt vmcnt(9)
	v_pk_fma_f32 v[52:53], v[42:43], v[108:109], v[216:217]
	v_pk_fma_f32 v[54:55], v[40:41], v[110:111], v[214:215]
	global_load_dwordx4 v[214:217], v[174:175], off offset:576
	s_waitcnt vmcnt(9)
	v_pk_fma_f32 v[56:57], v[34:35], v[108:109], v[226:227]
	v_pk_fma_f32 v[60:61], v[32:33], v[110:111], v[224:225]
	global_load_dwordx4 v[224:227], v[176:177], off offset:576
	s_waitcnt vmcnt(9)
	v_pk_fma_f32 v[48:49], v[26:27], v[108:109], v[230:231]
	v_pk_fma_f32 v[50:51], v[24:25], v[110:111], v[228:229]
	global_load_dwordx4 v[228:231], v[178:179], off offset:576
	s_waitcnt vmcnt(9)
	v_pk_fma_f32 v[40:41], v[18:19], v[108:109], v[234:235]
	v_pk_fma_f32 v[42:43], v[16:17], v[110:111], v[232:233]
	s_waitcnt vmcnt(8)
	v_pk_mul_f32 v[110:111], v[240:241], 0.5 op_sel_hi:[1, 0]
	v_pk_mul_f32 v[108:109], v[238:239], 0.5 op_sel_hi:[1, 0]
	s_waitcnt vmcnt(7)
	v_pk_fma_f32 v[24:25], v[46:47], v[110:111], v[250:251]
	v_pk_fma_f32 v[26:27], v[44:45], v[108:109], v[248:249]
	s_waitcnt vmcnt(6)
	v_pk_fma_f32 v[32:33], v[38:39], v[110:111], v[194:195]
	v_pk_fma_f32 v[34:35], v[36:37], v[108:109], v[192:193]
	s_waitcnt vmcnt(5)
	v_pk_fma_f32 v[16:17], v[30:31], v[110:111], v[198:199]
	v_pk_fma_f32 v[18:19], v[28:29], v[108:109], v[196:197]
	s_waitcnt vmcnt(4)
	v_pk_fma_f32 v[22:23], v[22:23], v[110:111], v[202:203]
	v_pk_fma_f32 v[20:21], v[20:21], v[108:109], v[200:201]
	s_waitcnt vmcnt(2)
	v_pk_fma_f32 v[14:15], v[14:15], v[110:111], v[216:217]
	v_pk_fma_f32 v[12:13], v[12:13], v[108:109], v[214:215]
	s_waitcnt vmcnt(1)
	v_pk_fma_f32 v[10:11], v[10:11], v[110:111], v[226:227]
	v_pk_fma_f32 v[8:9], v[8:9], v[108:109], v[224:225]
	s_waitcnt vmcnt(0)
	v_pk_fma_f32 v[6:7], v[6:7], v[110:111], v[230:231]
	v_pk_fma_f32 v[30:31], v[0:1], v[108:109], v[204:205]
	v_mul_f32_e32 v0, v163, v163
	v_mul_f32_e32 v1, v161, v161
	v_fmac_f32_e32 v0, v162, v162
	v_fmac_f32_e32 v1, v160, v160
	v_pk_fma_f32 v[4:5], v[4:5], v[108:109], v[228:229]
	v_pk_fma_f32 v[28:29], v[2:3], v[110:111], v[206:207]
	v_add_f32_e32 v0, v0, v1
	v_mul_f32_e32 v1, v107, v107
	v_mul_f32_e32 v2, v105, v105
	v_fmac_f32_e32 v1, v106, v106
	v_fmac_f32_e32 v2, v104, v104
	v_add_f32_e32 v1, v1, v2
	v_add_f32_e32 v0, v0, v1
	v_mul_f32_e32 v1, v67, v67
	v_mul_f32_e32 v2, v65, v65
	v_fmac_f32_e32 v1, v66, v66
	v_fmac_f32_e32 v2, v64, v64
	v_add_f32_e32 v1, v1, v2
	v_add_f32_e32 v0, v0, v1
	v_mul_f32_e32 v1, v27, v27
	v_mul_f32_e32 v2, v25, v25
	v_fmac_f32_e32 v1, v26, v26
	v_fmac_f32_e32 v2, v24, v24
	v_add_f32_e32 v1, v1, v2
	v_mul_f32_e32 v2, v159, v159
	v_mul_f32_e32 v3, v157, v157
	v_fmac_f32_e32 v2, v158, v158
	v_fmac_f32_e32 v3, v156, v156
	v_add_f32_e32 v2, v2, v3
	v_mul_f32_e32 v3, v101, v101
	v_mul_f32_e32 v36, v103, v103
	v_fmac_f32_e32 v3, v100, v100
	v_fmac_f32_e32 v36, v102, v102
	v_add_f32_e32 v3, v3, v36
	v_add_f32_e32 v2, v2, v3
	v_mul_f32_e32 v3, v75, v75
	v_mul_f32_e32 v36, v73, v73
	v_fmac_f32_e32 v3, v74, v74
	v_fmac_f32_e32 v36, v72, v72
	v_add_f32_e32 v3, v3, v36
	v_add_f32_e32 v2, v2, v3
	v_mul_f32_e32 v3, v35, v35
	v_mul_f32_e32 v36, v33, v33
	v_fmac_f32_e32 v3, v34, v34
	v_fmac_f32_e32 v36, v32, v32
	v_add_f32_e32 v3, v3, v36
	v_add_f32_e32 v0, v0, v1
	v_add3_u32 v1, s5, v186, v184
	v_add_f32_e32 v2, v2, v3
	ds_write2st64_b32 v1, v0, v2 offset1:4
	v_mul_f32_e32 v0, v147, v147
	v_mul_f32_e32 v2, v145, v145
	v_fmac_f32_e32 v0, v146, v146
	v_fmac_f32_e32 v2, v144, v144
	v_add_f32_e32 v0, v0, v2
	v_mul_f32_e32 v2, v93, v93
	v_mul_f32_e32 v3, v95, v95
	v_fmac_f32_e32 v2, v92, v92
	v_fmac_f32_e32 v3, v94, v94
	v_add_f32_e32 v2, v2, v3
	v_add_f32_e32 v0, v0, v2
	v_mul_f32_e32 v2, v63, v63
	v_mul_f32_e32 v3, v59, v59
	v_fmac_f32_e32 v2, v62, v62
	v_fmac_f32_e32 v3, v58, v58
	v_add_f32_e32 v2, v2, v3
	v_add_f32_e32 v0, v0, v2
	v_mul_f32_e32 v2, v19, v19
	v_mul_f32_e32 v3, v17, v17
	v_fmac_f32_e32 v2, v18, v18
	v_fmac_f32_e32 v3, v16, v16
	v_add_f32_e32 v2, v2, v3
	v_add_f32_e32 v0, v0, v2
	v_mul_f32_e32 v2, v153, v153
	v_mul_f32_e32 v3, v151, v151
	v_fmac_f32_e32 v2, v152, v152
	v_fmac_f32_e32 v3, v150, v150
	v_add_f32_e32 v2, v2, v3
	v_mul_f32_e32 v3, v99, v99
	v_mul_f32_e32 v36, v97, v97
	v_fmac_f32_e32 v3, v98, v98
	v_fmac_f32_e32 v36, v96, v96
	v_add_f32_e32 v3, v3, v36
	v_add_f32_e32 v2, v2, v3
	v_mul_f32_e32 v3, v71, v71
	v_mul_f32_e32 v36, v69, v69
	v_fmac_f32_e32 v3, v70, v70
	v_fmac_f32_e32 v36, v68, v68
	v_add_f32_e32 v3, v3, v36
	v_add_f32_e32 v2, v2, v3
	v_mul_f32_e32 v3, v21, v21
	v_mul_f32_e32 v36, v23, v23
	v_fmac_f32_e32 v3, v20, v20
	v_fmac_f32_e32 v36, v22, v22
	v_add_f32_e32 v3, v3, v36
	v_add_f32_e32 v2, v2, v3
	ds_write2st64_b32 v1, v0, v2 offset0:8 offset1:12
	v_mul_f32_e32 v0, v127, v127
	v_mul_f32_e32 v2, v125, v125
	v_fmac_f32_e32 v0, v126, v126
	v_fmac_f32_e32 v2, v124, v124
	v_add_f32_e32 v0, v0, v2
	v_mul_f32_e32 v2, v87, v87
	v_mul_f32_e32 v3, v85, v85
	v_fmac_f32_e32 v2, v86, v86
	v_fmac_f32_e32 v3, v84, v84
	v_add_f32_e32 v2, v2, v3
	v_add_f32_e32 v0, v0, v2
	v_mul_f32_e32 v2, v55, v55
	v_mul_f32_e32 v3, v53, v53
	v_fmac_f32_e32 v2, v54, v54
	v_fmac_f32_e32 v3, v52, v52
	v_add_f32_e32 v2, v2, v3
	v_add_f32_e32 v0, v0, v2
	v_mul_f32_e32 v2, v13, v13
	v_mul_f32_e32 v3, v15, v15
	v_fmac_f32_e32 v2, v12, v12
	v_fmac_f32_e32 v3, v14, v14
	v_add_f32_e32 v2, v2, v3
	v_add_f32_e32 v0, v0, v2
	v_mul_f32_e32 v2, v141, v141
	v_mul_f32_e32 v3, v139, v139
	v_fmac_f32_e32 v2, v140, v140
	v_fmac_f32_e32 v3, v138, v138
	v_add_f32_e32 v2, v2, v3
	v_mul_f32_e32 v3, v91, v91
	v_mul_f32_e32 v36, v89, v89
	v_fmac_f32_e32 v3, v90, v90
	v_fmac_f32_e32 v36, v88, v88
	v_add_f32_e32 v3, v3, v36
	v_add_f32_e32 v2, v2, v3
	v_mul_f32_e32 v3, v61, v61
	v_mul_f32_e32 v36, v57, v57
	v_fmac_f32_e32 v3, v60, v60
	v_fmac_f32_e32 v36, v56, v56
	v_add_f32_e32 v3, v3, v36
	v_add_f32_e32 v2, v2, v3
	v_mul_f32_e32 v3, v9, v9
	v_mul_f32_e32 v36, v11, v11
	v_fmac_f32_e32 v3, v8, v8
	v_fmac_f32_e32 v36, v10, v10
	v_add_f32_e32 v3, v3, v36
	v_add_f32_e32 v2, v2, v3
	ds_write2st64_b32 v1, v0, v2 offset0:32 offset1:36
	v_mul_f32_e32 v0, v123, v123
	v_mul_f32_e32 v2, v121, v121
	v_fmac_f32_e32 v0, v122, v122
	v_fmac_f32_e32 v2, v120, v120
	v_add_f32_e32 v0, v0, v2
	v_mul_f32_e32 v2, v83, v83
	v_mul_f32_e32 v3, v81, v81
	v_fmac_f32_e32 v2, v82, v82
	v_fmac_f32_e32 v3, v80, v80
	v_add_f32_e32 v2, v2, v3
	v_add_f32_e32 v0, v0, v2
	v_mul_f32_e32 v2, v51, v51
	v_mul_f32_e32 v3, v49, v49
	v_fmac_f32_e32 v2, v50, v50
	v_fmac_f32_e32 v3, v48, v48
	v_add_f32_e32 v2, v2, v3
	v_add_f32_e32 v0, v0, v2
	v_mul_f32_e32 v2, v5, v5
	v_mul_f32_e32 v3, v7, v7
	v_fmac_f32_e32 v2, v4, v4
	v_fmac_f32_e32 v3, v6, v6
	v_add_f32_e32 v2, v2, v3
	v_add_f32_e32 v0, v0, v2
	v_mul_f32_e32 v2, v119, v119
	v_mul_f32_e32 v3, v117, v117
	v_fmac_f32_e32 v2, v118, v118
	v_fmac_f32_e32 v3, v116, v116
	v_add_f32_e32 v2, v2, v3
	v_mul_f32_e32 v3, v79, v79
	v_mul_f32_e32 v36, v77, v77
	v_fmac_f32_e32 v3, v78, v78
	v_fmac_f32_e32 v36, v76, v76
	v_add_f32_e32 v3, v3, v36
	v_add_f32_e32 v2, v2, v3
	v_mul_f32_e32 v3, v43, v43
	v_mul_f32_e32 v36, v41, v41
	v_fmac_f32_e32 v3, v42, v42
	v_fmac_f32_e32 v36, v40, v40
	v_add_f32_e32 v3, v3, v36
	v_add_f32_e32 v2, v2, v3
	v_mul_f32_e32 v3, v31, v31
	v_mul_f32_e32 v36, v29, v29
	v_fmac_f32_e32 v3, v30, v30
	v_fmac_f32_e32 v36, v28, v28
	v_add_f32_e32 v3, v3, v36
	v_add_f32_e32 v2, v2, v3
	ds_write2st64_b32 v1, v0, v2 offset0:40 offset1:44
	s_waitcnt lgkmcnt(0)
	s_barrier
	v_and_b32_e32 v0, 31, v183
	v_lshl_or_b32 v2, s27, 5, v0
	v_lshl_add_u32 v0, s38, 8, v2
	s_and_saveexec_b64 s[8:9], s[6:7]
	s_cbranch_execz .LBB0_1738
	v_lshl_add_u32 v1, v2, 6, 0
	ds_read_b128 v[36:39], v1
	ds_read_b128 v[44:47], v1 offset:16
	ds_read_b128 v[108:111], v1 offset:32
	ds_read_b128 v[164:167], v1 offset:48
	s_ashr_i32 s41, s40, 31
	s_waitcnt lgkmcnt(3)
	v_add_f32_e32 v1, 0, v36
	v_add_f32_e32 v1, v1, v37
	v_add_f32_e32 v1, v1, v38
	v_add_f32_e32 v1, v1, v39
	s_waitcnt lgkmcnt(2)
	v_add_f32_e32 v1, v1, v44
	v_add_f32_e32 v1, v1, v45
	v_add_f32_e32 v1, v1, v46
	v_add_f32_e32 v1, v1, v47
	s_waitcnt lgkmcnt(1)
	v_add_f32_e32 v1, v1, v108
	v_add_f32_e32 v1, v1, v109
	v_add_f32_e32 v1, v1, v110
	v_add_f32_e32 v1, v1, v111
	s_waitcnt lgkmcnt(0)
	v_add_f32_e32 v1, v1, v164
	v_add_f32_e32 v1, v1, v165
	v_add_f32_e32 v1, v1, v166
	v_add_f32_e32 v3, v1, v167
	v_ashrrev_i32_e32 v1, 31, v0
	v_lshl_add_u64 v[36:37], v[0:1], 4, s[0:1]
	v_lshl_add_u64 v[36:37], s[40:41], 2, v[36:37]
	global_store_dword v[36:37], v3, off sc1
